# attention: staging write bases from the toggled read bases (1 instruction each), hipcc's redundant second zeroing of the O accumulators in the unit prologue removed
# baseline (speedup 1.0000x reference)
.LBB0_324:
	v_add_u32_e32 v1, 0x200, v1
	v_cmp_lt_u32_e32 vcc, s71, v1
	ds_write_b128 v0, v[240:243]
	s_or_b64 s[56:57], vcc, s[56:57]
	v_add_u32_e32 v0, 0x2000, v0
	s_andn2_b64 exec, exec, s[56:57]
	s_cbranch_execnz .LBB0_324
	s_or_b64 exec, exec, s[56:57]
	s_add_i32 s38, s54, 1
	v_cvt_f32_u32_e32 v0, s38
	v_mov_b32_e32 v63, 0
	v_mov_b32_e32 v62, v63
	v_mov_b32_e32 v61, v63
	v_mul_f32_e32 v1, -2.0, v0
	v_cmp_gt_f32_e32 vcc, s72, v1
	s_and_b64 s[56:57], vcc, exec
	s_cselect_b32 s38, 0xffffffc0, 0
	v_cndmask_b32_e32 v1, 0, v228, vcc
	v_fmac_f32_e32 v1, -2.0, v0
	v_exp_f32_e32 v0, v1
	s_sub_i32 s58, s89, 63
	v_cvt_f32_i32_e32 v2, s58
	v_mov_b32_e32 v60, v63
	v_ldexp_f32 v0, v0, s38
	v_mul_f32_e32 v201, 0x3fb8aa3b, v0
	v_div_scale_f32 v0, s[56:57], v201, v201, v213
	v_rcp_f32_e32 v1, v0
	v_div_scale_f32 v3, vcc, v213, v201, v213
	v_mov_b32_e32 v59, v63
	v_fma_f32 v4, -v0, v1, 1.0
	v_fmac_f32_e32 v1, v4, v1
	v_mul_f32_e32 v4, v3, v1
	v_fma_f32 v5, -v0, v4, v3
	v_fmac_f32_e32 v4, v5, v1
	v_fma_f32 v0, -v0, v4, v3
	v_div_fmas_f32 v0, v0, v1, v4
	v_div_fixup_f32 v0, v0, v201, v213
	v_sub_f32_e32 v0, v2, v0
	v_mul_f32_e32 v0, 0x3c800000, v0
	v_ceil_f32_e32 v1, v0
	v_cvt_i32_f32_e32 v1, v1
	v_cmp_lt_f32_e32 vcc, 0, v0
	v_mov_b32_e32 v58, v63
	v_mov_b32_e32 v57, v63
	v_readfirstlane_b32 s38, v1
	s_min_i32 s38, s38, s86
	s_and_b64 s[56:57], vcc, exec
	s_cselect_b32 s38, s38, 0
	s_sub_i32 s86, s86, s38
	s_add_i32 s38, s86, 2
	s_cmp_gt_i32 s38, -1
	v_mov_b32_e32 v56, v63
	v_mov_b32_e32 v55, v63
	v_mov_b32_e32 v54, v63
	v_mov_b32_e32 v53, v63
	v_mov_b32_e32 v52, v63
	v_mov_b32_e32 v51, v63
	v_mov_b32_e32 v50, v63
	v_mov_b32_e32 v49, v63
	v_mov_b32_e32 v48, v63
	v_mov_b32_e32 v47, v63
	v_mov_b32_e32 v46, v63
	v_mov_b32_e32 v45, v63
	v_mov_b32_e32 v44, v63
	v_mov_b32_e32 v43, v63
	v_mov_b32_e32 v42, v63
	v_mov_b32_e32 v41, v63
	v_mov_b32_e32 v40, v63
	v_mov_b32_e32 v39, v63
	v_mov_b32_e32 v38, v63
	v_mov_b32_e32 v37, v63
	v_mov_b32_e32 v36, v63
	v_mov_b32_e32 v35, v63
	v_mov_b32_e32 v34, v63
	v_mov_b32_e32 v33, v63
	v_mov_b32_e32 v32, v63
	v_mov_b32_e32 v31, v63
	v_mov_b32_e32 v30, v63
	v_mov_b32_e32 v29, v63
	v_mov_b32_e32 v28, v63
	v_mov_b32_e32 v27, v63
	v_mov_b32_e32 v26, v63
	v_mov_b32_e32 v25, v63
	v_mov_b32_e32 v24, v63
	v_mov_b32_e32 v23, v63
	v_mov_b32_e32 v22, v63
	v_mov_b32_e32 v21, v63
	v_mov_b32_e32 v20, v63
	v_mov_b32_e32 v19, v63
	v_mov_b32_e32 v18, v63
	v_mov_b32_e32 v17, v63
	v_mov_b32_e32 v16, v63
	v_mov_b32_e32 v15, v63
	v_mov_b32_e32 v14, v63
	v_mov_b32_e32 v13, v63
	v_mov_b32_e32 v12, v63
	v_mov_b32_e32 v11, v63
	v_mov_b32_e32 v10, v63
	v_mov_b32_e32 v9, v63
	v_mov_b32_e32 v8, v63
	v_mov_b32_e32 v7, v63
	v_mov_b32_e32 v6, v63
	v_mov_b32_e32 v5, v63
	v_mov_b32_e32 v4, v63
	v_mov_b32_e32 v3, v63
	v_mov_b32_e32 v2, v63
	v_mov_b32_e32 v1, v63
	v_mov_b32_e32 v0, v63
	v_mov_b32_e32 v233, v63
	s_waitcnt vmcnt(0)
	s_waitcnt lgkmcnt(0)
	s_barrier
	s_cbranch_scc0 .LBB0_347
	s_cmp_lt_u32 s84, 2
	s_cselect_b64 s[56:57], -1, 0
	s_lshl_b32 s33, s33, 1
	v_cndmask_b32_e64 v203, 0, 1, s[56:57]
	s_sub_i32 s56, 0, s33
	s_and_b32 s55, s55, 3
	s_ashr_i32 s57, s56, 31
	s_add_i32 s86, s86, 3
	s_lshl_b32 s55, s55, 14
	s_lshl_b64 s[92:93], s[56:57], 7
	s_add_u32 s33, s92, s55
	s_mul_i32 s59, s65, 0x10080
	s_addc_u32 s55, s93, 0
	s_mul_hi_u32 s58, s65, 0x10080
	s_add_u32 s92, s33, s59
	s_addc_u32 s93, s55, s58
	s_mov_b32 s55, s39
	s_mul_hi_i32 s33, s56, 0x50000
	s_mul_i32 s56, s56, 0x50000
	s_lshl_b64 s[54:55], s[54:55], 8
	s_add_u32 s54, s54, s56
	s_addc_u32 s33, s55, s33
	s_add_u32 s54, s54, s88
	v_mov_b32_e32 v80, v169
	v_mov_b32_e32 v81, v169
	s_addc_u32 s55, s33, 0
	v_mov_b32_e32 v82, v169
	v_mov_b32_e32 v83, v169
	v_mov_b32_e32 v84, v169
	v_mov_b32_e32 v85, v169
	v_mov_b32_e32 v86, v169
	v_mov_b32_e32 v87, v169
	v_mov_b32_e32 v88, v169
	v_mov_b32_e32 v89, v169
	v_mov_b32_e32 v90, v169
	v_mov_b32_e32 v91, v169
	v_mov_b32_e32 v92, v169
	v_mov_b32_e32 v93, v169
	v_mov_b32_e32 v94, v169
	v_mov_b32_e32 v95, v169
	v_mov_b32_e32 v233, 0
	v_mov_b32_e32 v64, v253
	v_mov_b32_e32 v65, v253
	v_lshl_add_u32 v230, s85, 7, v214
	s_mov_b32 s90, 0
	v_lshl_add_u64 v[204:205], s[92:93], 0, v[198:199]
	v_lshl_add_u64 v[206:207], s[54:55], 0, v[170:171]
	v_add_u32_e32 v231, s87, v225
	v_mov_b32_e32 v144, 0
	v_mov_b32_e32 v145, 0
	v_mov_b32_e32 v146, 0
	v_mov_b32_e32 v147, 0
	v_mov_b32_e32 v148, 0
	v_mov_b32_e32 v149, 0
	v_mov_b32_e32 v150, 0
	v_mov_b32_e32 v151, 0
	v_mov_b32_e32 v66, v253
	v_mov_b32_e32 v67, v253
	v_mov_b32_e32 v68, v253
	v_mov_b32_e32 v69, v253
	v_mov_b32_e32 v70, v253
	v_mov_b32_e32 v71, v253
	v_mov_b32_e32 v72, v253
	v_mov_b32_e32 v73, v253
	v_mov_b32_e32 v74, v253
	v_mov_b32_e32 v75, v253
	v_mov_b32_e32 v76, v253
	v_mov_b32_e32 v77, v253
	v_mov_b32_e32 v78, v253
	v_mov_b32_e32 v79, v253
	v_mov_b32_e32 v232, 0
	s_cmp_lg_u64 s[98:99], 0
	s_cbranch_scc1 .Lan_entry

.Lan_entry:
	v_cvt_f32_i32_e32 v255, v231
	v_add_f32_e32 v255, 0x42800000, v255
	v_cmp_eq_u32_e32 vcc, 0, v203
	s_nop 1
	v_cndmask_b32_e32 v208, v229, v255, vcc
	v_add_f32_e32 v255, 0x80000000, v208
	v_fma_f32 v96, -v201, |v255|, v253
	v_add_f32_e32 v255, 0xbf800000, v208
	v_fma_f32 v97, -v201, |v255|, v253
	v_add_f32_e32 v255, 0xc0000000, v208
	v_fma_f32 v98, -v201, |v255|, v253
	v_add_f32_e32 v255, 0xc0400000, v208
	v_fma_f32 v99, -v201, |v255|, v253
	v_add_f32_e32 v255, 0xc0800000, v208
	v_fma_f32 v100, -v201, |v255|, v253
	v_add_f32_e32 v255, 0xc0a00000, v208
	v_fma_f32 v101, -v201, |v255|, v253
	v_add_f32_e32 v255, 0xc0c00000, v208
	v_fma_f32 v102, -v201, |v255|, v253
	v_add_f32_e32 v255, 0xc0e00000, v208
	v_fma_f32 v103, -v201, |v255|, v253
	v_add_f32_e32 v255, 0xc1800000, v208
	v_fma_f32 v104, -v201, |v255|, v253
	v_add_f32_e32 v255, 0xc1880000, v208
	v_fma_f32 v105, -v201, |v255|, v253
	v_add_f32_e32 v255, 0xc1900000, v208
	v_fma_f32 v106, -v201, |v255|, v253
	v_add_f32_e32 v255, 0xc1980000, v208
	v_fma_f32 v107, -v201, |v255|, v253
	v_add_f32_e32 v255, 0xc1a00000, v208
	v_fma_f32 v108, -v201, |v255|, v253
	v_add_f32_e32 v255, 0xc1a80000, v208
	v_fma_f32 v109, -v201, |v255|, v253
	v_add_f32_e32 v255, 0xc1b00000, v208
	v_fma_f32 v110, -v201, |v255|, v253
	v_add_f32_e32 v255, 0xc1b80000, v208
	v_fma_f32 v111, -v201, |v255|, v253
	v_mov_b32_e32 v80, 0xff61b1e6
	v_mov_b32_e32 v81, 0xff61b1e6
	v_mov_b32_e32 v82, 0xff61b1e6
	v_mov_b32_e32 v83, 0xff61b1e6
	v_mov_b32_e32 v84, 0xff61b1e6
	v_mov_b32_e32 v85, 0xff61b1e6
	v_mov_b32_e32 v86, 0xff61b1e6
	v_mov_b32_e32 v87, 0xff61b1e6
	v_mov_b32_e32 v88, 0xff61b1e6
	v_mov_b32_e32 v89, 0xff61b1e6
	v_mov_b32_e32 v90, 0xff61b1e6
	v_mov_b32_e32 v91, 0xff61b1e6
	v_mov_b32_e32 v92, 0xff61b1e6
	v_mov_b32_e32 v93, 0xff61b1e6
	v_mov_b32_e32 v94, 0xff61b1e6
	v_mov_b32_e32 v95, 0xff61b1e6
	s_add_u32 s94, s62, 0x8f61000
	s_addc_u32 s95, s63, 0
	s_add_u32 s96, s62, 0x18803000
	s_addc_u32 s97, s63, 0
	v_lshl_add_u64 v[206:207], v[206:207], 0, s[94:95]
	v_lshl_add_u64 v[204:205], v[204:205], 0, s[96:97]
	s_mov_b32 s94, 0x28000
	s_mov_b32 s95, 0
	s_mov_b32 s96, 0x402000
	s_mov_b32 s97, 0
	v_mov_b32_e32 v235, v230
	v_add_u32_e32 v234, 0x4800, v215
	v_lshlrev_b32_e32 v248, 1, v230
	v_add_u32_e32 v248, 0x4400, v248
	v_lshlrev_b32_e32 v249, 1, v215
	v_add_u32_e32 v249, 0x4800, v249
	v_xor_b32_e32 v236, 0x80000000, v201
	v_sub_u32_e32 v250, v212, v230
	v_sub_u32_e32 v251, v222, v215
	s_cmp_eq_u32 s85, 1
	s_cbranch_scc1 .Lan_327_h1

.LfixB_skip_h0:
	v_sub_u32_e32 v235, v248, v235
	v_sub_u32_e32 v234, v249, v234
	s_andn2_b64 vcc, exec, s[54:55]
	s_cbranch_vccnz .Lan_343_h0
	v_add_u32_e32 v255, v250, v235
	s_waitcnt vmcnt(1)
	ds_write_b128 v255, v[128:131]
	s_waitcnt vmcnt(0)
	ds_write_b128 v255, v[132:135] offset:8704
.Lan_343_h0:
	s_andn2_b64 vcc, exec, s[56:57]
	s_cbranch_vccnz .Lan_345_h0
	v_add_u32_e32 v255, v251, v234
	s_waitcnt vmcnt(1)
	ds_write_b128 v255, v[136:139] offset:34816
	s_waitcnt vmcnt(0)
	ds_write_b128 v255, v[140:143] offset:44032
.Lan_345_h0:
	v_lshl_add_u64 v[204:205], v[204:205], 0, s[30:31]
	v_lshl_add_u64 v[206:207], v[206:207], 0, s[44:45]
	s_cmp_eq_u32 s86, s87
	v_add_u32_e32 v231, 64, v231
	s_waitcnt lgkmcnt(0)
	s_barrier
	s_cbranch_scc1 .LBB0_347
	s_mov_b32 s90, s87
	s_branch .Lan_327_h0
.Lan_327_h1:
	s_add_i32 s87, s90, 1
	ds_read_b128 v[64:67], v235
	ds_read_b128 v[68:71], v235 offset:32
	ds_read_b128 v[72:75], v235 offset:64
	ds_read_b128 v[76:79], v235 offset:96
	ds_read_b128 v[160:163], v234 offset:34816
	s_cmp_lt_i32 s87, s38
	s_cselect_b64 s[54:55], -1, 0
	s_cbranch_scc0 .Lan_329_h1
	v_lshl_add_u64 v[244:245], v[206:207], 0, s[94:95]
	global_load_dwordx4 v[128:131], v[206:207], off
	global_load_dwordx4 v[132:135], v[244:245], off
